# final rmsnorm phase: gain vector hoisted out of the row loop, next row prefetched before the stores, no drain waits
# speedup vs baseline: 1.0125x; 1.0005x over previous
; __device__ __forceinline__ float sumsq4(f32x4 v) { return (v[0] * v[0] + v[1] * v[1]) + (v[2] * v[2] + v[3] * v[3]); }
; __device__ __forceinline__ void unpack8(u32x4 w, f32x4& a, f32x4& b) { a = (f32x4){bf_lo(w.x), bf_hi(w.x), bf_lo(w.y), bf_hi(w.y)}; b = (f32x4){bf_lo(w.z), bf_hi(w.z), bf_lo(w.w), bf_hi(w.w)}; }
; __global__ void __launch_bounds__(NWAVES * 64, 2) fwd_mega(Args a) {
;     ...
;     {
;         PHASE_PTRS();
;         const float* gn = a.in[20];
;         for (int m = gw; m < T; m += ngw) {
;             f32x4 v[8]; float sq = 0.f;
; #pragma unroll
;             for (int j = 0; j < 4; ++j) { unpack8(*(const u32x4*)(X1B + (size_t)m * DM + j * 512 + lane * 8), v[2 * j], v[2 * j + 1]); sq += sumsq4(v[2 * j]) + sumsq4(v[2 * j + 1]); }
;             const float rs = rsqrtf(wave_sum(sq) * (1.0f / DM) + EPS);
;             float* orow = a.out + (size_t)m * DM;
; #pragma unroll
;             for (int j = 0; j < 4; ++j) { const int c = j * 512 + lane * 8;
;                 *(f32x4*)(orow + c) = v[2 * j] * rs * *(const f32x4*)(gn + c); *(f32x4*)(orow + c + 4) = v[2 * j + 1] * rs * *(const f32x4*)(gn + c + 4); }
;         }
.LBB0_1241:
	s_or_b64 exec, exec, s[0:1]
	s_mov_b64 s[4:5], 0
	s_and_b64 vcc, exec, s[2:3]
	s_waitcnt lgkmcnt(0)
	s_barrier
	s_cbranch_vccnz .LBB0_1244
	v_lshlrev_b32_e32 v0, 5, v253
	v_readlane_b32 s0, v255, 0
	v_and_b32_e32 v8, 0x7e0, v0
	v_mov_b32_e32 v9, 0
	v_readlane_b32 s1, v255, 1
	v_or_b32_e32 v2, 0x1000, v8
	v_mov_b32_e32 v3, v9
	v_lshl_add_u64 v[0:1], s[0:1], 0, v[8:9]
	v_or_b32_e32 v8, 0x1800, v8
	s_ashr_i32 s11, s10, 31
	v_readlane_b32 s2, v255, 2
	v_lshl_add_u64 v[2:3], s[0:1], 0, v[2:3]
	v_lshl_add_u64 v[4:5], s[0:1], 0, v[8:9]
	s_lshl_b64 s[0:1], s[10:11], 13
	v_readlane_b32 s3, v255, 3
	v_and_b32_e32 v10, 63, v253
	s_add_u32 s0, s2, s0
	v_lshlrev_b32_e32 v8, 5, v10
	s_addc_u32 s1, s3, s1
	v_lshl_add_u64 v[6:7], s[0:1], 0, v[8:9]
	s_mov_b64 s[0:1], 0x1810
	s_ashr_i32 s35, s34, 31
	v_lshl_add_u64 v[6:7], v[6:7], 0, s[0:1]
	s_lshl_b64 s[0:1], s[34:35], 13
	s_lshl_b64 s[2:3], s[10:11], 12
	s_add_u32 s2, s4, s2
	s_addc_u32 s3, s5, s3
	s_add_u32 s2, s60, s2
	v_lshlrev_b32_e32 v8, 4, v10
	s_addc_u32 s3, s61, s3
	v_lshl_add_u64 v[8:9], s[2:3], 0, v[8:9]
	s_mov_b64 s[2:3], 0x3500800
	v_lshl_add_u64 v[8:9], v[8:9], 0, s[2:3]
	s_lshl_b64 s[2:3], s[34:35], 12
	v_mov_b32_e32 v10, 0x358637bd
	s_mov_b32 s4, 0x800000
	s_movk_i32 s5, 0xf000
	global_load_dwordx4 v[98:101], v[8:9], off offset:-2048
	global_load_dwordx4 v[102:105], v[8:9], off offset:-1024
	global_load_dwordx4 v[106:109], v[8:9], off
	global_load_dwordx4 v[110:113], v[8:9], off offset:1024
	global_load_dwordx4 v[66:69], v[0:1], off
	global_load_dwordx4 v[70:73], v[0:1], off offset:16
	global_load_dwordx4 v[74:77], v[0:1], off offset:2048
	global_load_dwordx4 v[78:81], v[0:1], off offset:2064
	global_load_dwordx4 v[82:85], v[2:3], off
	global_load_dwordx4 v[86:89], v[2:3], off offset:16
	global_load_dwordx4 v[90:93], v[4:5], off
	global_load_dwordx4 v[94:97], v[4:5], off offset:16
; __device__ __forceinline__ float sumsq4(f32x4 v) { return (v[0] * v[0] + v[1] * v[1]) + (v[2] * v[2] + v[3] * v[3]); }
; __device__ __forceinline__ void unpack8(u32x4 w, f32x4& a, f32x4& b) { a = (f32x4){bf_lo(w.x), bf_hi(w.x), bf_lo(w.y), bf_hi(w.y)}; b = (f32x4){bf_lo(w.z), bf_hi(w.z), bf_lo(w.w), bf_hi(w.w)}; }
; __global__ void __launch_bounds__(NWAVES * 64, 2) fwd_mega(Args a) {
;     ...
;         for (int m = gw; m < T; m += ngw) {
;             f32x4 v[8]; float sq = 0.f;
; #pragma unroll
;             for (int j = 0; j < 4; ++j) { unpack8(*(const u32x4*)(X1B + (size_t)m * DM + j * 512 + lane * 8), v[2 * j], v[2 * j + 1]); sq += sumsq4(v[2 * j]) + sumsq4(v[2 * j + 1]); }
;             const float rs = rsqrtf(wave_sum(sq) * (1.0f / DM) + EPS);
;             float* orow = a.out + (size_t)m * DM;
; #pragma unroll
;             for (int j = 0; j < 4; ++j) { const int c = j * 512 + lane * 8;
;                 *(f32x4*)(orow + c) = v[2 * j] * rs * *(const f32x4*)(gn + c); *(f32x4*)(orow + c + 4) = v[2 * j + 1] * rs * *(const f32x4*)(gn + c + 4); }
;         }
.LBB0_1243:
	v_add_co_u32_e32 v32, vcc, s5, v6
	s_add_i32 s10, s10, s34
	s_nop 0
	v_addc_co_u32_e32 v33, vcc, -1, v7, vcc
	v_lshl_add_u64 v[8:9], v[8:9], 0, s[2:3]
	s_cmpk_lt_i32 s10, 0x6000
	s_waitcnt vmcnt(11)
	v_lshlrev_b32_e32 v34, 16, v98
	v_and_b32_e32 v35, 0xffff0000, v98
	v_lshlrev_b32_e32 v12, 16, v99
	v_and_b32_e32 v13, 0xffff0000, v99
	v_and_b32_e32 v37, 0xffff0000, v100
	v_lshlrev_b32_e32 v38, 16, v101
	s_waitcnt vmcnt(10)
	v_lshlrev_b32_e32 v40, 16, v102
	v_and_b32_e32 v41, 0xffff0000, v102
	v_lshlrev_b32_e32 v16, 16, v103
	v_and_b32_e32 v17, 0xffff0000, v103
	v_lshlrev_b32_e32 v42, 16, v104
	v_and_b32_e32 v43, 0xffff0000, v104
	v_lshlrev_b32_e32 v18, 16, v105
	v_lshlrev_b32_e32 v36, 16, v100
	v_and_b32_e32 v39, 0xffff0000, v101
	v_and_b32_e32 v19, 0xffff0000, v105
	s_waitcnt vmcnt(9)
	v_lshlrev_b32_e32 v44, 16, v106
	v_and_b32_e32 v45, 0xffff0000, v106
	v_lshlrev_b32_e32 v20, 16, v107
	v_and_b32_e32 v21, 0xffff0000, v107
	v_lshlrev_b32_e32 v46, 16, v108
	v_and_b32_e32 v47, 0xffff0000, v108
	v_lshlrev_b32_e32 v22, 16, v109
	v_mul_f32_e32 v11, v35, v35
	v_mul_f32_e32 v14, v13, v13
	v_mul_f32_e32 v15, v37, v37
	v_mul_f32_e32 v52, v38, v38
	v_mul_f32_e32 v53, v41, v41
	v_mul_f32_e32 v54, v17, v17
	v_mul_f32_e32 v55, v43, v43
	v_mul_f32_e32 v56, v18, v18
	v_and_b32_e32 v23, 0xffff0000, v109
	s_waitcnt vmcnt(8)
	v_lshlrev_b32_e32 v48, 16, v110
	v_and_b32_e32 v49, 0xffff0000, v110
	v_lshlrev_b32_e32 v24, 16, v111
	v_and_b32_e32 v25, 0xffff0000, v111
	v_lshlrev_b32_e32 v50, 16, v112
	v_and_b32_e32 v51, 0xffff0000, v112
	v_lshlrev_b32_e32 v26, 16, v113
	v_mul_f32_e32 v57, v45, v45
	v_mul_f32_e32 v58, v21, v21
	v_mul_f32_e32 v59, v47, v47
	v_mul_f32_e32 v60, v22, v22
	v_fmac_f32_e32 v11, v34, v34
	v_fmac_f32_e32 v14, v12, v12
	v_fmac_f32_e32 v15, v36, v36
	v_fmac_f32_e32 v52, v39, v39
	v_fmac_f32_e32 v53, v40, v40
	v_fmac_f32_e32 v54, v16, v16
	v_fmac_f32_e32 v55, v42, v42
	v_fmac_f32_e32 v56, v19, v19
	v_and_b32_e32 v27, 0xffff0000, v113
	global_load_dwordx4 v[98:101], v[8:9], off offset:-2048
	global_load_dwordx4 v[102:105], v[8:9], off offset:-1024
	global_load_dwordx4 v[106:109], v[8:9], off
	global_load_dwordx4 v[110:113], v[8:9], off offset:1024
	v_mul_f32_e32 v61, v49, v49
	v_mul_f32_e32 v62, v25, v25
	v_mul_f32_e32 v63, v51, v51
	v_mul_f32_e32 v64, v26, v26
	v_fmac_f32_e32 v57, v44, v44
	v_fmac_f32_e32 v58, v20, v20
	v_fmac_f32_e32 v59, v46, v46
	v_fmac_f32_e32 v60, v23, v23
	v_add_f32_e32 v11, v11, v14
	v_add_f32_e32 v14, v15, v52
	v_add_f32_e32 v15, v53, v54
	v_add_f32_e32 v52, v55, v56
	v_fmac_f32_e32 v61, v48, v48
	v_fmac_f32_e32 v62, v24, v24
	v_fmac_f32_e32 v63, v50, v50
	v_fmac_f32_e32 v64, v27, v27
	v_add_f32_e32 v53, v57, v58
	v_add_f32_e32 v54, v59, v60
	v_add_f32_e32 v11, v11, v14
	v_add_f32_e32 v14, v15, v52
	v_add_f32_e32 v55, v61, v62
	v_add_f32_e32 v56, v63, v64
	v_add_f32_e32 v15, v53, v54
	v_add_f32_e32 v11, v11, v14
	v_add_f32_e32 v52, v55, v56
	v_add_f32_e32 v11, v11, v15
	v_add_f32_e32 v11, v11, v52
	ds_swizzle_b32 v14, v11 offset:swizzle(SWAP,1)
	s_waitcnt lgkmcnt(0)
	v_add_f32_e32 v11, v11, v14
	ds_swizzle_b32 v14, v11 offset:swizzle(SWAP,2)
	s_waitcnt lgkmcnt(0)
	v_add_f32_e32 v11, v11, v14
	ds_swizzle_b32 v14, v11 offset:swizzle(SWAP,4)
	s_waitcnt lgkmcnt(0)
	v_add_f32_e32 v11, v11, v14
	ds_swizzle_b32 v14, v11 offset:swizzle(SWAP,8)
	s_waitcnt lgkmcnt(0)
	v_add_f32_e32 v11, v11, v14
	ds_swizzle_b32 v14, v11 offset:swizzle(SWAP,16)
	s_waitcnt lgkmcnt(0)
	v_add_f32_e32 v11, v11, v14
	v_mov_b32_e32 v14, v11
	s_nop 1
	v_permlane32_swap_b32_e32 v11, v14
	v_add_f32_e32 v11, v11, v14
	v_fmamk_f32 v11, v11, 0x3a000000, v10
	v_mul_f32_e32 v14, 0x4b800000, v11
	v_cmp_gt_f32_e32 vcc, s4, v11
	s_nop 1
	v_cndmask_b32_e32 v11, v11, v14, vcc
	v_rsq_f32_e32 v11, v11
	s_nop 0
	v_mul_f32_e32 v14, 0x45800000, v11
	v_cndmask_b32_e32 v52, v11, v14, vcc
	v_pk_mul_f32 v[34:35], v[52:53], v[34:35] op_sel_hi:[0,1]
	v_pk_mul_f32 v[12:13], v[52:53], v[12:13] op_sel_hi:[0,1]
	s_waitcnt vmcnt(4)
	v_pk_mul_f32 v[14:15], v[12:13], v[68:69]
	v_pk_mul_f32 v[12:13], v[34:35], v[66:67]
	global_store_dwordx4 v[32:33], v[12:15], off offset:-2064
	s_nop 0
	v_pk_mul_f32 v[28:29], v[52:53], v[38:39] op_sel_hi:[0,1]
	v_pk_mul_f32 v[30:31], v[52:53], v[36:37] op_sel_hi:[0,1]
	v_pk_mul_f32 v[16:17], v[52:53], v[16:17] op_sel_hi:[0,1]
	v_pk_mul_f32 v[12:13], v[30:31], v[70:71]
	v_pk_mul_f32 v[14:15], v[28:29], v[72:73]
	global_store_dwordx4 v[32:33], v[12:15], off offset:-2048
	s_nop 0
	v_pk_mul_f32 v[28:29], v[52:53], v[40:41] op_sel_hi:[0,1]
	v_pk_mul_f32 v[12:13], v[28:29], v[74:75]
	v_pk_mul_f32 v[14:15], v[16:17], v[76:77]
	global_store_dwordx4 v[32:33], v[12:15], off offset:-16
	s_nop 0
	v_pk_mul_f32 v[16:17], v[52:53], v[18:19] op_sel_hi:[0,1]
	v_pk_mul_f32 v[18:19], v[52:53], v[42:43] op_sel_hi:[0,1]
	v_pk_mul_f32 v[12:13], v[18:19], v[78:79]
	v_pk_mul_f32 v[14:15], v[16:17], v[80:81]
	global_store_dwordx4 v[6:7], v[12:15], off offset:-4096
	s_nop 0
	v_pk_mul_f32 v[16:17], v[52:53], v[20:21] op_sel_hi:[0,1]
	v_pk_mul_f32 v[18:19], v[52:53], v[44:45] op_sel_hi:[0,1]
	v_pk_mul_f32 v[12:13], v[18:19], v[82:83]
	v_pk_mul_f32 v[14:15], v[16:17], v[84:85]
	global_store_dwordx4 v[6:7], v[12:15], off offset:-2064
	s_nop 0
	v_pk_mul_f32 v[16:17], v[52:53], v[22:23] op_sel_hi:[0,1]
	v_pk_mul_f32 v[18:19], v[52:53], v[46:47] op_sel_hi:[0,1]
	v_pk_mul_f32 v[12:13], v[18:19], v[86:87]
	v_pk_mul_f32 v[14:15], v[16:17], v[88:89]
	global_store_dwordx4 v[6:7], v[12:15], off offset:-2048
	s_nop 0
	v_pk_mul_f32 v[16:17], v[52:53], v[24:25] op_sel_hi:[0,1]
	v_pk_mul_f32 v[18:19], v[52:53], v[48:49] op_sel_hi:[0,1]
	v_pk_mul_f32 v[12:13], v[18:19], v[90:91]
	v_pk_mul_f32 v[14:15], v[16:17], v[92:93]
	global_store_dwordx4 v[6:7], v[12:15], off offset:-16
	s_nop 0
	v_pk_mul_f32 v[16:17], v[52:53], v[26:27] op_sel_hi:[0,1]
	v_pk_mul_f32 v[18:19], v[52:53], v[50:51] op_sel_hi:[0,1]
	v_pk_mul_f32 v[12:13], v[18:19], v[94:95]
	v_pk_mul_f32 v[14:15], v[16:17], v[96:97]
	global_store_dwordx4 v[6:7], v[12:15], off
	v_lshl_add_u64 v[6:7], v[6:7], 0, s[0:1]
	s_cbranch_scc1 .LBB0_1243
